# static s_setprio 1 for waves 0-3 limited to the K-loop (dropped to 0 during epilogues, re-raised per tile)
# baseline (speedup 1.0000x reference)
; __device__ __forceinline__ void gemm_phase(LAS unsigned char* lds, CParams& p, const Job& jb) {
;     ...
;     for (;;) {
;         const bool has_next = S.next(ui + 1, nxt);
;         const char* nA = has_next ? nxt.A : cA; const char* nB = has_next ? nxt.B : cB;
;         for (int t = 0; t < nt; t += 2) {
.LBB0_630:
	s_cmp_lg_u32 s0, 0
	s_cbranch_scc1 .Lprio_tile
	s_setprio 1

; #define PG8_STAGE(bufoff, gbase, voff) do { _Pragma("unroll") for (int _i = 0; _i < 2; ++_i) \
;         __builtin_amdgcn_global_load_lds((const unsigned*)((const char*)(gbase) + (voff)[_i]), (LAS unsigned*)(lds + (bufoff) + ldsw + _i * 8192), 16, 0, 0); } while (0)
; #define PG8_LDA(dst, b, h) do { _Pragma("unroll") for (int m = 0; m < 4; ++m) _Pragma("unroll") for (int k = 0; k < 2; ++k) dst[m][k] = *(const LAS bf16x8*)(lds + PG8_SA(b, h) + aoff + m * 2048 + k * 1024); } while (0)
; #define PG8_LDB(dst, b, h) do { _Pragma("unroll") for (int n = 0; n < 2; ++n) _Pragma("unroll") for (int k = 0; k < 2; ++k) dst[n][k] = *(const LAS bf16x8*)(lds + PG8_SB(b, h) + boff + n * 2048 + k * 1024); } while (0)
; #define PG8_MMA(ai, bj, At, Bt) do { __builtin_amdgcn_s_setprio(1); _Pragma("unroll") for (int m = 0; m < 4; ++m) _Pragma("unroll") for (int n = 0; n < 2; ++n) _Pragma("unroll") for (int k = 0; k < 2; ++k) \
;         acc[ai][bj][m][n] = __builtin_amdgcn_mfma_f32_16x16x32_bf16(Bt[n][k], At[m][k], acc[ai][bj][m][n], 0, 0, 0); __builtin_amdgcn_s_setprio(0); } while (0)
; #define PG8_WAIT_L(n) asm volatile("s_waitcnt lgkmcnt(" #n ")" ::: "memory")
; #define PG8_BAR __builtin_amdgcn_s_barrier()
; #define PG8_SCHED __builtin_amdgcn_sched_barrier(0)
; __device__ __forceinline__ void gemm_phase(LAS unsigned char* lds, CParams& p, const Job& jb) {
;     ...
;         for (int t = 0; t < nt; t += 2) {
;             const bool last = (t == nt - 2);
;             const char* a1 = cA + (size_t)(t + 1) * kstep;
;             const char* a2 = last ? nA : cA + (size_t)(t + 2) * kstep; const char* b2 = last ? nB : cB + (size_t)(t + 2) * kstep;
;             const char* a3 = a2 + kstep; const char* b3 = b2 + kstep;
;             PG8_LDB(B0, 0, 0); PG8_SCHED; PG8_LDA(At, 0, 0); PG8_STAGE(PG8_SA(1, 1), a1 + hstepA, voffA);
;             PG8_WAIT_L(8); PG8_BAR; PG8_WAIT_L(0); PG8_MMA(0, 0, At, B0); PG8_BAR; PG8_SCHED;
;             PG8_LDB(B1, 0, 1); PG8_STAGE(PG8_SB(0, 0), b2, voffB);
;             PG8_BAR; PG8_WAIT_L(0); PG8_MMA(0, 1, At, B1); PG8_BAR;
;             PG8_LDA(At, 0, 1); PG8_STAGE(PG8_SA(0, 0), a2, voffA);
;             PG8_BAR; PG8_WAIT_L(0); PG8_MMA(1, 0, At, B0); PG8_BAR; PG8_SCHED;
.LBB0_631:
	s_add_i32 s1, s1, 2
	s_add_u32 s12, s24, s10
	s_addc_u32 s13, s25, s11
	s_add_u32 s12, s12, 0x100
	s_addc_u32 s13, s13, 0
	s_add_u32 s14, s97, s10
	s_addc_u32 s15, s2, s11
	s_add_i32 s16, 0, 0x10000
	v_add_u32_e32 v144, s16, v213
	ds_read_b128 v[132:135], v144
	ds_read_b128 v[136:139], v144 offset:1024
	ds_read_b128 v[140:143], v144 offset:2048
	ds_read_b128 v[144:147], v144 offset:3072
	s_cmp_eq_u32 s85, s10
	s_cselect_b32 s13, s5, s13
	s_cselect_b32 s12, s4, s12
	s_cselect_b32 s15, s87, s15
	s_cselect_b32 s14, s86, s14
	v_lshl_add_u64 v[216:217], v[128:129], 0, s[10:11]
	s_add_i32 m0, s65, 0xc000
	ds_read_b128 v[148:151], v214
	ds_read_b128 v[152:155], v214 offset:1024
	ds_read_b128 v[156:159], v214 offset:2048
	ds_read_b128 v[172:175], v214 offset:3072
	ds_read_b128 v[176:179], v214 offset:4096
	ds_read_b128 v[180:183], v214 offset:5120
	ds_read_b128 v[184:187], v214 offset:6144
	ds_read_b128 v[188:191], v214 offset:7168
	global_load_lds_dwordx4 v[216:217], off
	v_lshl_add_u64 v[216:217], v[130:131], 0, s[10:11]
	s_add_i32 m0, s65, 0xe000
	s_nop 0
	global_load_lds_dwordx4 v[216:217], off
	s_waitcnt lgkmcnt(8)
	s_barrier
	s_waitcnt lgkmcnt(0)
	s_waitcnt lgkmcnt(0)
	v_mfma_f32_16x16x32_bf16 v[124:127], v[132:135], v[148:151], v[124:127]
	v_mfma_f32_16x16x32_bf16 v[120:123], v[140:143], v[148:151], v[120:123]
	v_mfma_f32_16x16x32_bf16 v[116:119], v[132:135], v[156:159], v[116:119]
	v_mfma_f32_16x16x32_bf16 v[112:115], v[140:143], v[156:159], v[112:115]
	v_mfma_f32_16x16x32_bf16 v[108:111], v[132:135], v[176:179], v[108:111]
	v_mfma_f32_16x16x32_bf16 v[104:107], v[140:143], v[176:179], v[104:107]
	v_mfma_f32_16x16x32_bf16 v[100:103], v[132:135], v[184:187], v[100:103]
	v_mfma_f32_16x16x32_bf16 v[96:99], v[140:143], v[184:187], v[96:99]
	v_mfma_f32_16x16x32_bf16 v[124:127], v[136:139], v[152:155], v[124:127]
	v_mfma_f32_16x16x32_bf16 v[120:123], v[144:147], v[152:155], v[120:123]
	v_mfma_f32_16x16x32_bf16 v[116:119], v[136:139], v[172:175], v[116:119]
	v_mfma_f32_16x16x32_bf16 v[112:115], v[144:147], v[172:175], v[112:115]
	v_mfma_f32_16x16x32_bf16 v[108:111], v[136:139], v[180:183], v[108:111]
	v_mfma_f32_16x16x32_bf16 v[104:107], v[144:147], v[180:183], v[104:107]
	v_mfma_f32_16x16x32_bf16 v[100:103], v[136:139], v[188:191], v[100:103]
	v_mfma_f32_16x16x32_bf16 v[96:99], v[144:147], v[188:191], v[96:99]
	s_barrier
	s_add_i32 s17, 0, 0x14000
	s_add_i32 s16, s16, s64
	v_add_u32_e32 v215, s17, v213
	v_lshl_add_u64 v[232:233], s[14:15], 0, v[160:161]
	s_mov_b32 m0, s16
	ds_read_b128 v[216:219], v215
	ds_read_b128 v[220:223], v215 offset:1024
	ds_read_b128 v[224:227], v215 offset:2048
	ds_read_b128 v[228:231], v215 offset:3072
	global_load_lds_dwordx4 v[232:233], off
	v_lshl_add_u64 v[234:235], s[14:15], 0, v[166:167]
	s_add_i32 m0, s16, 0x2000
	s_nop 0
	global_load_lds_dwordx4 v[234:235], off
	s_barrier
	s_waitcnt lgkmcnt(0)
	s_waitcnt lgkmcnt(0)
	v_mfma_f32_16x16x32_bf16 v[92:95], v[216:219], v[148:151], v[92:95]
	v_mfma_f32_16x16x32_bf16 v[88:91], v[224:227], v[148:151], v[88:91]
	v_mfma_f32_16x16x32_bf16 v[84:87], v[216:219], v[156:159], v[84:87]
	v_mfma_f32_16x16x32_bf16 v[80:83], v[224:227], v[156:159], v[80:83]
	v_mfma_f32_16x16x32_bf16 v[76:79], v[216:219], v[176:179], v[76:79]
	v_mfma_f32_16x16x32_bf16 v[72:75], v[224:227], v[176:179], v[72:75]
	v_mfma_f32_16x16x32_bf16 v[68:71], v[216:219], v[184:187], v[68:71]
	v_mfma_f32_16x16x32_bf16 v[64:67], v[224:227], v[184:187], v[64:67]
	v_mfma_f32_16x16x32_bf16 v[92:95], v[220:223], v[152:155], v[92:95]
	v_mfma_f32_16x16x32_bf16 v[88:91], v[228:231], v[152:155], v[88:91]
	v_mfma_f32_16x16x32_bf16 v[84:87], v[220:223], v[172:175], v[84:87]
	v_mfma_f32_16x16x32_bf16 v[80:83], v[228:231], v[172:175], v[80:83]
	v_mfma_f32_16x16x32_bf16 v[76:79], v[220:223], v[180:183], v[76:79]
	v_mfma_f32_16x16x32_bf16 v[72:75], v[228:231], v[180:183], v[72:75]
	v_mfma_f32_16x16x32_bf16 v[68:71], v[220:223], v[188:191], v[68:71]
	v_mfma_f32_16x16x32_bf16 v[64:67], v[228:231], v[188:191], v[64:67]
	s_mov_b32 m0, s65
	v_lshl_add_u64 v[236:237], s[12:13], 0, v[162:163]
	s_barrier
	ds_read_b128 v[148:151], v214 offset:16384
	ds_read_b128 v[152:155], v214 offset:17408
	ds_read_b128 v[156:159], v214 offset:18432
	ds_read_b128 v[172:175], v214 offset:19456
	ds_read_b128 v[176:179], v214 offset:20480
	ds_read_b128 v[180:183], v214 offset:21504
	ds_read_b128 v[184:187], v214 offset:22528
	ds_read_b128 v[188:191], v214 offset:23552
	global_load_lds_dwordx4 v[236:237], off
	v_lshl_add_u64 v[238:239], s[12:13], 0, v[164:165]
	s_mov_b32 m0, s66
	s_nop 0
	global_load_lds_dwordx4 v[238:239], off
	s_barrier
	s_waitcnt lgkmcnt(0)
	s_waitcnt lgkmcnt(0)
	v_mfma_f32_16x16x32_bf16 v[60:63], v[132:135], v[148:151], v[60:63]
	v_mfma_f32_16x16x32_bf16 v[56:59], v[140:143], v[148:151], v[56:59]
	v_mfma_f32_16x16x32_bf16 v[52:55], v[132:135], v[156:159], v[52:55]
	v_mfma_f32_16x16x32_bf16 v[48:51], v[140:143], v[156:159], v[48:51]
	v_mfma_f32_16x16x32_bf16 v[44:47], v[132:135], v[176:179], v[44:47]
	v_mfma_f32_16x16x32_bf16 v[40:43], v[140:143], v[176:179], v[40:43]
	v_mfma_f32_16x16x32_bf16 v[36:39], v[132:135], v[184:187], v[36:39]
	v_mfma_f32_16x16x32_bf16 v[32:35], v[140:143], v[184:187], v[32:35]
	v_mfma_f32_16x16x32_bf16 v[60:63], v[136:139], v[152:155], v[60:63]
	v_mfma_f32_16x16x32_bf16 v[56:59], v[144:147], v[152:155], v[56:59]
	v_mfma_f32_16x16x32_bf16 v[52:55], v[136:139], v[172:175], v[52:55]
	v_mfma_f32_16x16x32_bf16 v[48:51], v[144:147], v[172:175], v[48:51]
	v_mfma_f32_16x16x32_bf16 v[44:47], v[136:139], v[180:183], v[44:47]
	v_mfma_f32_16x16x32_bf16 v[40:43], v[144:147], v[180:183], v[40:43]
	v_mfma_f32_16x16x32_bf16 v[36:39], v[136:139], v[188:191], v[36:39]
	v_mfma_f32_16x16x32_bf16 v[32:35], v[144:147], v[188:191], v[32:35]
	s_barrier
; #define PG8_STAGE(bufoff, gbase, voff) do { _Pragma("unroll") for (int _i = 0; _i < 2; ++_i) \
;         __builtin_amdgcn_global_load_lds((const unsigned*)((const char*)(gbase) + (voff)[_i]), (LAS unsigned*)(lds + (bufoff) + ldsw + _i * 8192), 16, 0, 0); } while (0)
; #define PG8_LDA(dst, b, h) do { _Pragma("unroll") for (int m = 0; m < 4; ++m) _Pragma("unroll") for (int k = 0; k < 2; ++k) dst[m][k] = *(const LAS bf16x8*)(lds + PG8_SA(b, h) + aoff + m * 2048 + k * 1024); } while (0)
; #define PG8_LDB(dst, b, h) do { _Pragma("unroll") for (int n = 0; n < 2; ++n) _Pragma("unroll") for (int k = 0; k < 2; ++k) dst[n][k] = *(const LAS bf16x8*)(lds + PG8_SB(b, h) + boff + n * 2048 + k * 1024); } while (0)
; #define PG8_MMA(ai, bj, At, Bt) do { __builtin_amdgcn_s_setprio(1); _Pragma("unroll") for (int m = 0; m < 4; ++m) _Pragma("unroll") for (int n = 0; n < 2; ++n) _Pragma("unroll") for (int k = 0; k < 2; ++k) \
;         acc[ai][bj][m][n] = __builtin_amdgcn_mfma_f32_16x16x32_bf16(Bt[n][k], At[m][k], acc[ai][bj][m][n], 0, 0, 0); __builtin_amdgcn_s_setprio(0); } while (0)
; #define PG8_WAIT_V(n) asm volatile("s_waitcnt vmcnt(" #n ")" ::: "memory")
; #define PG8_WAIT_L(n) asm volatile("s_waitcnt lgkmcnt(" #n ")" ::: "memory")
; #define PG8_BAR __builtin_amdgcn_s_barrier()
; #define PG8_SCHED __builtin_amdgcn_sched_barrier(0)
; __device__ __forceinline__ void gemm_phase(LAS unsigned char* lds, CParams& p, const Job& jb) {
;     ...
;             PG8_STAGE(PG8_SB(0, 1), b2 + hstepB, voffB);
;             PG8_WAIT_V(6); PG8_BAR; PG8_MMA(1, 1, At, B1); PG8_BAR;
;             PG8_LDB(B0, 1, 0); PG8_SCHED; PG8_LDA(At, 1, 0); PG8_STAGE(PG8_SA(0, 1), a2 + hstepA, voffA);
;             PG8_WAIT_L(8); PG8_BAR; PG8_WAIT_L(0); PG8_MMA(0, 0, At, B0); PG8_BAR; PG8_SCHED;
;             PG8_LDB(B1, 1, 1); PG8_STAGE(PG8_SB(1, 0), b3, voffB);
;             PG8_BAR; PG8_WAIT_L(0); PG8_MMA(0, 1, At, B1); PG8_BAR;
;             PG8_LDA(At, 1, 1); PG8_STAGE(PG8_SA(1, 0), a3, voffA);
	s_add_u32 s14, s14, s76
	s_addc_u32 s15, s15, s77
	s_add_i32 s16, s17, s64
	v_lshl_add_u64 v[240:241], s[14:15], 0, v[160:161]
	s_mov_b32 m0, s16
	v_lshl_add_u64 v[242:243], s[14:15], 0, v[166:167]
	global_load_lds_dwordx4 v[240:241], off
	s_add_i32 m0, s16, 0x2000
	s_nop 0
	global_load_lds_dwordx4 v[242:243], off
	s_waitcnt vmcnt(6)
	s_barrier
	v_mfma_f32_16x16x32_bf16 v[28:31], v[216:219], v[148:151], v[28:31]
	v_mfma_f32_16x16x32_bf16 v[24:27], v[224:227], v[148:151], v[24:27]
	v_mfma_f32_16x16x32_bf16 v[20:23], v[216:219], v[156:159], v[20:23]
	v_mfma_f32_16x16x32_bf16 v[16:19], v[224:227], v[156:159], v[16:19]
	v_mfma_f32_16x16x32_bf16 v[12:15], v[216:219], v[176:179], v[12:15]
	v_mfma_f32_16x16x32_bf16 v[8:11], v[224:227], v[176:179], v[8:11]
	v_mfma_f32_16x16x32_bf16 v[4:7], v[216:219], v[184:187], v[4:7]
	v_mfma_f32_16x16x32_bf16 v[0:3], v[224:227], v[184:187], v[0:3]
	v_mfma_f32_16x16x32_bf16 v[28:31], v[220:223], v[152:155], v[28:31]
	v_mfma_f32_16x16x32_bf16 v[24:27], v[228:231], v[152:155], v[24:27]
	v_mfma_f32_16x16x32_bf16 v[20:23], v[220:223], v[172:175], v[20:23]
	v_mfma_f32_16x16x32_bf16 v[16:19], v[228:231], v[172:175], v[16:19]
	v_mfma_f32_16x16x32_bf16 v[12:15], v[220:223], v[180:183], v[12:15]
	v_mfma_f32_16x16x32_bf16 v[8:11], v[228:231], v[180:183], v[8:11]
	v_mfma_f32_16x16x32_bf16 v[4:7], v[220:223], v[188:191], v[4:7]
	v_mfma_f32_16x16x32_bf16 v[0:3], v[228:231], v[188:191], v[0:3]
	s_add_i32 s14, 0, 0x18000
	v_add_u32_e32 v144, s14, v213
	s_barrier
	ds_read_b128 v[132:135], v144
	ds_read_b128 v[136:139], v144 offset:1024
	ds_read_b128 v[140:143], v144 offset:2048
	ds_read_b128 v[144:147], v144 offset:3072
	s_add_u32 s12, s12, s74
	s_addc_u32 s13, s13, s75
	s_mov_b32 m0, s67
	v_lshl_add_u64 v[216:217], s[12:13], 0, v[162:163]
	ds_read_b128 v[148:151], v214 offset:32768
	ds_read_b128 v[152:155], v214 offset:33792
	ds_read_b128 v[156:159], v214 offset:34816
	ds_read_b128 v[172:175], v214 offset:35840
	ds_read_b128 v[176:179], v214 offset:36864
	ds_read_b128 v[180:183], v214 offset:37888
	ds_read_b128 v[184:187], v214 offset:38912
	ds_read_b128 v[188:191], v214 offset:39936
	global_load_lds_dwordx4 v[216:217], off
	v_lshl_add_u64 v[216:217], s[12:13], 0, v[164:165]
	s_mov_b32 m0, s94
	s_nop 0
	global_load_lds_dwordx4 v[216:217], off
	s_waitcnt lgkmcnt(8)
	s_barrier
	s_waitcnt lgkmcnt(0)
	s_waitcnt lgkmcnt(0)
	v_mfma_f32_16x16x32_bf16 v[124:127], v[132:135], v[148:151], v[124:127]
	v_mfma_f32_16x16x32_bf16 v[120:123], v[140:143], v[148:151], v[120:123]
	v_mfma_f32_16x16x32_bf16 v[116:119], v[132:135], v[156:159], v[116:119]
	v_mfma_f32_16x16x32_bf16 v[112:115], v[140:143], v[156:159], v[112:115]
	v_mfma_f32_16x16x32_bf16 v[108:111], v[132:135], v[176:179], v[108:111]
	v_mfma_f32_16x16x32_bf16 v[104:107], v[140:143], v[176:179], v[104:107]
	v_mfma_f32_16x16x32_bf16 v[100:103], v[132:135], v[184:187], v[100:103]
	v_mfma_f32_16x16x32_bf16 v[96:99], v[140:143], v[184:187], v[96:99]
	v_mfma_f32_16x16x32_bf16 v[124:127], v[136:139], v[152:155], v[124:127]
	v_mfma_f32_16x16x32_bf16 v[120:123], v[144:147], v[152:155], v[120:123]
	v_mfma_f32_16x16x32_bf16 v[116:119], v[136:139], v[172:175], v[116:119]
	v_mfma_f32_16x16x32_bf16 v[112:115], v[144:147], v[172:175], v[112:115]
	v_mfma_f32_16x16x32_bf16 v[108:111], v[136:139], v[180:183], v[108:111]
	v_mfma_f32_16x16x32_bf16 v[104:107], v[144:147], v[180:183], v[104:107]
	v_mfma_f32_16x16x32_bf16 v[100:103], v[136:139], v[188:191], v[100:103]
	v_mfma_f32_16x16x32_bf16 v[96:99], v[144:147], v[188:191], v[96:99]
	s_barrier
	s_add_i32 s12, 0, 0x1c000
	s_add_i32 s13, s14, s64
	v_add_u32_e32 v215, s12, v213
	v_lshl_add_u64 v[232:233], v[232:233], 0, s[90:91]
	s_mov_b32 m0, s13
	ds_read_b128 v[216:219], v215
	ds_read_b128 v[220:223], v215 offset:1024
	ds_read_b128 v[224:227], v215 offset:2048
	ds_read_b128 v[228:231], v215 offset:3072
	global_load_lds_dwordx4 v[232:233], off
	v_lshl_add_u64 v[232:233], v[234:235], 0, s[90:91]
	s_add_i32 m0, s13, 0x2000
	s_nop 0
	global_load_lds_dwordx4 v[232:233], off
	s_barrier
	s_waitcnt lgkmcnt(0)
	s_waitcnt lgkmcnt(0)
	v_mfma_f32_16x16x32_bf16 v[92:95], v[216:219], v[148:151], v[92:95]
	v_mfma_f32_16x16x32_bf16 v[88:91], v[224:227], v[148:151], v[88:91]
	v_mfma_f32_16x16x32_bf16 v[84:87], v[216:219], v[156:159], v[84:87]
	v_mfma_f32_16x16x32_bf16 v[80:83], v[224:227], v[156:159], v[80:83]
	v_mfma_f32_16x16x32_bf16 v[76:79], v[216:219], v[176:179], v[76:79]
	v_mfma_f32_16x16x32_bf16 v[72:75], v[224:227], v[176:179], v[72:75]
	v_mfma_f32_16x16x32_bf16 v[68:71], v[216:219], v[184:187], v[68:71]
	v_mfma_f32_16x16x32_bf16 v[64:67], v[224:227], v[184:187], v[64:67]
	v_mfma_f32_16x16x32_bf16 v[92:95], v[220:223], v[152:155], v[92:95]
	v_mfma_f32_16x16x32_bf16 v[88:91], v[228:231], v[152:155], v[88:91]
	v_mfma_f32_16x16x32_bf16 v[84:87], v[220:223], v[172:175], v[84:87]
	v_mfma_f32_16x16x32_bf16 v[80:83], v[228:231], v[172:175], v[80:83]
	v_mfma_f32_16x16x32_bf16 v[76:79], v[220:223], v[180:183], v[76:79]
	v_mfma_f32_16x16x32_bf16 v[72:75], v[228:231], v[180:183], v[72:75]
	v_mfma_f32_16x16x32_bf16 v[68:71], v[220:223], v[188:191], v[68:71]
	v_mfma_f32_16x16x32_bf16 v[64:67], v[228:231], v[188:191], v[64:67]
	s_mov_b32 m0, s33
	v_lshl_add_u64 v[232:233], v[236:237], 0, s[90:91]
	s_barrier
	ds_read_b128 v[148:151], v214 offset:49152
	ds_read_b128 v[152:155], v214 offset:50176
	ds_read_b128 v[156:159], v214 offset:51200
	ds_read_b128 v[172:175], v214 offset:52224
	ds_read_b128 v[176:179], v214 offset:53248
	ds_read_b128 v[180:183], v214 offset:54272
	ds_read_b128 v[184:187], v214 offset:55296
	ds_read_b128 v[188:191], v214 offset:56320
	global_load_lds_dwordx4 v[232:233], off
	v_lshl_add_u64 v[232:233], v[238:239], 0, s[90:91]
	s_mov_b32 m0, s60
	s_nop 0
	global_load_lds_dwordx4 v[232:233], off
	s_barrier
; #define FOR_ROWS _Pragma("unroll") for (int ai = 0; ai < 2; ++ai) _Pragma("unroll") for (int m = 0; m < 4; ++m)
; #define PG8_STAGE(bufoff, gbase, voff) do { _Pragma("unroll") for (int _i = 0; _i < 2; ++_i) \
;         __builtin_amdgcn_global_load_lds((const unsigned*)((const char*)(gbase) + (voff)[_i]), (LAS unsigned*)(lds + (bufoff) + ldsw + _i * 8192), 16, 0, 0); } while (0)
; #define PG8_MMA(ai, bj, At, Bt) do { __builtin_amdgcn_s_setprio(1); _Pragma("unroll") for (int m = 0; m < 4; ++m) _Pragma("unroll") for (int n = 0; n < 2; ++n) _Pragma("unroll") for (int k = 0; k < 2; ++k) \
;         acc[ai][bj][m][n] = __builtin_amdgcn_mfma_f32_16x16x32_bf16(Bt[n][k], At[m][k], acc[ai][bj][m][n], 0, 0, 0); __builtin_amdgcn_s_setprio(0); } while (0)
; #define PG8_WAIT_V(n) asm volatile("s_waitcnt vmcnt(" #n ")" ::: "memory")
; #define PG8_WAIT_L(n) asm volatile("s_waitcnt lgkmcnt(" #n ")" ::: "memory")
; #define PG8_BAR __builtin_amdgcn_s_barrier()
; #define PG8_SCHED __builtin_amdgcn_sched_barrier(0)
; __device__ __forceinline__ void epilogue(const int kind, CParams& p, const f32x4 (&acc)[2][2][4][2], const Unit& u, const int wr, const int wc, const int fr_in, const int fq_in) {
;     ...
;     case E_DOWN_HALF: {
;         FOR_ROWS { ROWDEF
; #pragma unroll
;             for (int bj = 0; bj < 2; ++bj) { float* hp = p.out + row * 1024 + u.pn * 256 + bj * 128 + cw;
; #pragma unroll
;                 for (int j = 0; j < 4; ++j) { unsafeAtomicAdd(hp + j, acc[ai][bj][m][0][j]); unsafeAtomicAdd(hp + 4 + j, acc[ai][bj][m][1][j]); } } }
;     } break;
; __device__ __forceinline__ void gemm_phase(LAS unsigned char* lds, CParams& p, const Job& jb) {
;     ...
;             PG8_BAR; PG8_WAIT_L(0); PG8_MMA(1, 0, At, B0); PG8_BAR; PG8_SCHED;
;             PG8_STAGE(PG8_SB(1, 1), b3 + hstepB, voffB);
;             PG8_WAIT_V(6); PG8_BAR; PG8_MMA(1, 1, At, B1); PG8_BAR;
;         }
;         epilogue(cur.kind, p, acc, cur, wr, wc, fr, fq);
	s_waitcnt lgkmcnt(0)
	s_waitcnt lgkmcnt(0)
	v_mfma_f32_16x16x32_bf16 v[60:63], v[132:135], v[148:151], v[60:63]
	v_mfma_f32_16x16x32_bf16 v[56:59], v[140:143], v[148:151], v[56:59]
	v_mfma_f32_16x16x32_bf16 v[52:55], v[132:135], v[156:159], v[52:55]
	v_mfma_f32_16x16x32_bf16 v[48:51], v[140:143], v[156:159], v[48:51]
	v_mfma_f32_16x16x32_bf16 v[44:47], v[132:135], v[176:179], v[44:47]
	v_mfma_f32_16x16x32_bf16 v[40:43], v[140:143], v[176:179], v[40:43]
	v_mfma_f32_16x16x32_bf16 v[36:39], v[132:135], v[184:187], v[36:39]
	v_mfma_f32_16x16x32_bf16 v[32:35], v[140:143], v[184:187], v[32:35]
	v_mfma_f32_16x16x32_bf16 v[60:63], v[136:139], v[152:155], v[60:63]
	v_mfma_f32_16x16x32_bf16 v[56:59], v[144:147], v[152:155], v[56:59]
	v_mfma_f32_16x16x32_bf16 v[52:55], v[136:139], v[172:175], v[52:55]
	v_mfma_f32_16x16x32_bf16 v[48:51], v[144:147], v[172:175], v[48:51]
	v_mfma_f32_16x16x32_bf16 v[44:47], v[136:139], v[180:183], v[44:47]
	v_mfma_f32_16x16x32_bf16 v[40:43], v[144:147], v[180:183], v[40:43]
	v_mfma_f32_16x16x32_bf16 v[36:39], v[136:139], v[188:191], v[36:39]
	v_mfma_f32_16x16x32_bf16 v[32:35], v[144:147], v[188:191], v[32:35]
	s_barrier
	s_add_i32 s12, s12, s64
	v_lshl_add_u64 v[132:133], v[240:241], 0, s[90:91]
	s_mov_b32 m0, s12
	s_nop 0
	global_load_lds_dwordx4 v[132:133], off
	v_lshl_add_u64 v[132:133], v[242:243], 0, s[90:91]
	s_add_i32 m0, s12, 0x2000
	s_nop 0
	global_load_lds_dwordx4 v[132:133], off
	s_waitcnt vmcnt(6)
	s_barrier
	v_mfma_f32_16x16x32_bf16 v[28:31], v[216:219], v[148:151], v[28:31]
	v_mfma_f32_16x16x32_bf16 v[24:27], v[224:227], v[148:151], v[24:27]
	v_mfma_f32_16x16x32_bf16 v[20:23], v[216:219], v[156:159], v[20:23]
	v_mfma_f32_16x16x32_bf16 v[16:19], v[224:227], v[156:159], v[16:19]
	v_mfma_f32_16x16x32_bf16 v[12:15], v[216:219], v[176:179], v[12:15]
	v_mfma_f32_16x16x32_bf16 v[8:11], v[224:227], v[176:179], v[8:11]
	v_mfma_f32_16x16x32_bf16 v[4:7], v[216:219], v[184:187], v[4:7]
	v_mfma_f32_16x16x32_bf16 v[0:3], v[224:227], v[184:187], v[0:3]
	v_mfma_f32_16x16x32_bf16 v[28:31], v[220:223], v[152:155], v[28:31]
	v_mfma_f32_16x16x32_bf16 v[24:27], v[228:231], v[152:155], v[24:27]
	v_mfma_f32_16x16x32_bf16 v[20:23], v[220:223], v[172:175], v[20:23]
	v_mfma_f32_16x16x32_bf16 v[16:19], v[228:231], v[172:175], v[16:19]
	v_mfma_f32_16x16x32_bf16 v[12:15], v[220:223], v[180:183], v[12:15]
	v_mfma_f32_16x16x32_bf16 v[8:11], v[228:231], v[180:183], v[8:11]
	v_mfma_f32_16x16x32_bf16 v[4:7], v[220:223], v[188:191], v[4:7]
	v_mfma_f32_16x16x32_bf16 v[0:3], v[228:231], v[188:191], v[0:3]
	s_add_u32 s10, s10, 0x100
	s_addc_u32 s11, s11, 0
	s_cmp_ge_u32 s1, s84
	s_barrier
	s_cbranch_scc0 .LBB0_631
	s_setprio 0
	v_mov_b32_e32 v215, v211
	v_mov_b32_e32 v216, v212
	s_cmp_eq_u32 s3, 13
	s_cbranch_scc1 .Lmy_down
	s_cmp_eq_u32 s3, 12
	s_cbranch_scc1 .Lmy_ffn1
	s_cmp_lt_i32 s3, 7
	v_lshl_add_u32 v172, v216, 3, s31
	s_mov_b64 s[10:11], -1
	s_cbranch_scc1 .LBB0_849
	s_cmp_lt_i32 s3, 11
	s_cbranch_scc1 .LBB0_639
	s_cmp_gt_i32 s3, 12
	s_cbranch_scc0 .LBB0_640
	s_cmp_gt_i32 s3, 13
	s_mov_b64 s[26:27], -1
	s_cbranch_scc0 .LBB0_641
	s_cmp_eq_u32 s3, 14
	s_cbranch_scc0 .LBB0_638
	v_add_u32_e32 v128, s0, v215
	s_ashr_i32 s79, s78, 31
	v_ashrrev_i32_e32 v129, 31, v128
	v_lshl_add_u64 v[130:131], v[128:129], 0, s[78:79]
	s_lshl_b32 s10, s92, 8
	v_lshlrev_b64 v[130:131], 12, v[130:131]
	s_ashr_i32 s11, s10, 31
	v_ashrrev_i32_e32 v173, 31, v172
	v_lshl_add_u64 v[130:131], s[82:83], 0, v[130:131]
	s_lshl_b64 s[10:11], s[10:11], 2
	v_lshl_add_u64 v[130:131], v[130:131], 0, s[10:11]
	v_lshlrev_b64 v[132:133], 2, v[172:173]
	v_lshl_add_u64 v[130:131], v[130:131], 0, v[132:133]
	global_atomic_add_f32 v[130:131], v124, off
	global_atomic_add_f32 v[130:131], v120, off offset:16
	global_atomic_add_f32 v[130:131], v125, off offset:4
	global_atomic_add_f32 v[130:131], v121, off offset:20
	global_atomic_add_f32 v[130:131], v126, off offset:8
	global_atomic_add_f32 v[130:131], v122, off offset:24
	global_atomic_add_f32 v[130:131], v127, off offset:12
	global_atomic_add_f32 v[130:131], v123, off offset:28
	global_atomic_add_f32 v[130:131], v92, off offset:512
	global_atomic_add_f32 v[130:131], v88, off offset:528
	global_atomic_add_f32 v[130:131], v93, off offset:516
	global_atomic_add_f32 v[130:131], v89, off offset:532
	global_atomic_add_f32 v[130:131], v94, off offset:520
	global_atomic_add_f32 v[130:131], v90, off offset:536
	global_atomic_add_f32 v[130:131], v95, off offset:524
	global_atomic_add_f32 v[130:131], v91, off offset:540
	v_add_u32_e32 v130, 16, v128
	v_ashrrev_i32_e32 v131, 31, v130
	v_lshl_add_u64 v[130:131], v[130:131], 0, s[78:79]
	v_lshlrev_b64 v[130:131], 12, v[130:131]
	v_lshl_add_u64 v[130:131], s[82:83], 0, v[130:131]
	v_lshl_add_u64 v[130:131], v[130:131], 0, s[10:11]
	v_lshl_add_u64 v[130:131], v[130:131], 0, v[132:133]
	global_atomic_add_f32 v[130:131], v116, off
	global_atomic_add_f32 v[130:131], v112, off offset:16
	global_atomic_add_f32 v[130:131], v117, off offset:4
	global_atomic_add_f32 v[130:131], v113, off offset:20
	global_atomic_add_f32 v[130:131], v118, off offset:8
	global_atomic_add_f32 v[130:131], v114, off offset:24
	global_atomic_add_f32 v[130:131], v119, off offset:12
	global_atomic_add_f32 v[130:131], v115, off offset:28
	global_atomic_add_f32 v[130:131], v84, off offset:512
	global_atomic_add_f32 v[130:131], v80, off offset:528
	global_atomic_add_f32 v[130:131], v85, off offset:516
	global_atomic_add_f32 v[130:131], v81, off offset:532
	global_atomic_add_f32 v[130:131], v86, off offset:520
	global_atomic_add_f32 v[130:131], v82, off offset:536
	global_atomic_add_f32 v[130:131], v87, off offset:524
; #define FOR_ROWS _Pragma("unroll") for (int ai = 0; ai < 2; ++ai) _Pragma("unroll") for (int m = 0; m < 4; ++m)
; __device__ __forceinline__ void epilogue(const int kind, CParams& p, const f32x4 (&acc)[2][2][4][2], const Unit& u, const int wr, const int wc, const int fr_in, const int fq_in) {
;     ...
;     case E_DOWN_HALF: {
;         FOR_ROWS { ROWDEF
; #pragma unroll
;             for (int bj = 0; bj < 2; ++bj) { float* hp = p.out + row * 1024 + u.pn * 256 + bj * 128 + cw;
; #pragma unroll
;                 for (int j = 0; j < 4; ++j) { unsafeAtomicAdd(hp + j, acc[ai][bj][m][0][j]); unsafeAtomicAdd(hp + 4 + j, acc[ai][bj][m][1][j]); } } }
;     } break;
	global_atomic_add_f32 v[130:131], v83, off offset:540
	v_add_u32_e32 v130, 32, v128
	v_ashrrev_i32_e32 v131, 31, v130
	v_lshl_add_u64 v[130:131], v[130:131], 0, s[78:79]
	v_lshlrev_b64 v[130:131], 12, v[130:131]
	v_lshl_add_u64 v[130:131], s[82:83], 0, v[130:131]
	v_lshl_add_u64 v[130:131], v[130:131], 0, s[10:11]
	v_lshl_add_u64 v[130:131], v[130:131], 0, v[132:133]
	global_atomic_add_f32 v[130:131], v108, off
	global_atomic_add_f32 v[130:131], v104, off offset:16
	global_atomic_add_f32 v[130:131], v109, off offset:4
	global_atomic_add_f32 v[130:131], v105, off offset:20
	global_atomic_add_f32 v[130:131], v110, off offset:8
	global_atomic_add_f32 v[130:131], v106, off offset:24
	global_atomic_add_f32 v[130:131], v111, off offset:12
	global_atomic_add_f32 v[130:131], v107, off offset:28
	global_atomic_add_f32 v[130:131], v76, off offset:512
	global_atomic_add_f32 v[130:131], v72, off offset:528
	global_atomic_add_f32 v[130:131], v77, off offset:516
	global_atomic_add_f32 v[130:131], v73, off offset:532
	global_atomic_add_f32 v[130:131], v78, off offset:520
	global_atomic_add_f32 v[130:131], v74, off offset:536
	global_atomic_add_f32 v[130:131], v79, off offset:524
	global_atomic_add_f32 v[130:131], v75, off offset:540
	v_add_u32_e32 v130, 48, v128
	v_ashrrev_i32_e32 v131, 31, v130
	v_lshl_add_u64 v[130:131], v[130:131], 0, s[78:79]
	v_lshlrev_b64 v[130:131], 12, v[130:131]
	v_lshl_add_u64 v[130:131], s[82:83], 0, v[130:131]
	v_lshl_add_u64 v[130:131], v[130:131], 0, s[10:11]
	v_lshl_add_u64 v[130:131], v[130:131], 0, v[132:133]
	global_atomic_add_f32 v[130:131], v100, off
	global_atomic_add_f32 v[130:131], v96, off offset:16
	global_atomic_add_f32 v[130:131], v101, off offset:4
	global_atomic_add_f32 v[130:131], v97, off offset:20
	global_atomic_add_f32 v[130:131], v102, off offset:8
	global_atomic_add_f32 v[130:131], v98, off offset:24
	global_atomic_add_f32 v[130:131], v103, off offset:12
	global_atomic_add_f32 v[130:131], v99, off offset:28
	global_atomic_add_f32 v[130:131], v68, off offset:512
	global_atomic_add_f32 v[130:131], v64, off offset:528
	global_atomic_add_f32 v[130:131], v69, off offset:516
	global_atomic_add_f32 v[130:131], v65, off offset:532
	global_atomic_add_f32 v[130:131], v70, off offset:520
	global_atomic_add_f32 v[130:131], v66, off offset:536
	global_atomic_add_f32 v[130:131], v71, off offset:524
	global_atomic_add_f32 v[130:131], v67, off offset:540
	v_add_u32_e32 v130, 0x80, v128
	v_ashrrev_i32_e32 v131, 31, v130
	v_lshl_add_u64 v[130:131], v[130:131], 0, s[78:79]
	v_lshlrev_b64 v[130:131], 12, v[130:131]
	v_lshl_add_u64 v[130:131], s[82:83], 0, v[130:131]
	v_lshl_add_u64 v[130:131], v[130:131], 0, s[10:11]
	v_lshl_add_u64 v[130:131], v[130:131], 0, v[132:133]
	global_atomic_add_f32 v[130:131], v60, off
	global_atomic_add_f32 v[130:131], v56, off offset:16
	global_atomic_add_f32 v[130:131], v61, off offset:4
	global_atomic_add_f32 v[130:131], v57, off offset:20
	global_atomic_add_f32 v[130:131], v62, off offset:8
	global_atomic_add_f32 v[130:131], v58, off offset:24
	global_atomic_add_f32 v[130:131], v63, off offset:12
	global_atomic_add_f32 v[130:131], v59, off offset:28
	global_atomic_add_f32 v[130:131], v28, off offset:512
	global_atomic_add_f32 v[130:131], v24, off offset:528
	global_atomic_add_f32 v[130:131], v29, off offset:516
	global_atomic_add_f32 v[130:131], v25, off offset:532
	global_atomic_add_f32 v[130:131], v30, off offset:520
	global_atomic_add_f32 v[130:131], v26, off offset:536
	global_atomic_add_f32 v[130:131], v31, off offset:524
; #define FOR_ROWS _Pragma("unroll") for (int ai = 0; ai < 2; ++ai) _Pragma("unroll") for (int m = 0; m < 4; ++m)
; __device__ __forceinline__ void epilogue(const int kind, CParams& p, const f32x4 (&acc)[2][2][4][2], const Unit& u, const int wr, const int wc, const int fr_in, const int fq_in) {
;     ...
;     case E_DOWN_HALF: {
;         FOR_ROWS { ROWDEF
; #pragma unroll
;             for (int bj = 0; bj < 2; ++bj) { float* hp = p.out + row * 1024 + u.pn * 256 + bj * 128 + cw;
; #pragma unroll
;                 for (int j = 0; j < 4; ++j) { unsafeAtomicAdd(hp + j, acc[ai][bj][m][0][j]); unsafeAtomicAdd(hp + 4 + j, acc[ai][bj][m][1][j]); } } }
;     } break;
	global_atomic_add_f32 v[130:131], v27, off offset:540
	v_add_u32_e32 v130, 0x90, v128
	v_ashrrev_i32_e32 v131, 31, v130
	v_lshl_add_u64 v[130:131], v[130:131], 0, s[78:79]
	v_lshlrev_b64 v[130:131], 12, v[130:131]
	v_lshl_add_u64 v[130:131], s[82:83], 0, v[130:131]
	v_lshl_add_u64 v[130:131], v[130:131], 0, s[10:11]
	v_lshl_add_u64 v[130:131], v[130:131], 0, v[132:133]
	global_atomic_add_f32 v[130:131], v52, off
	global_atomic_add_f32 v[130:131], v48, off offset:16
	global_atomic_add_f32 v[130:131], v53, off offset:4
	global_atomic_add_f32 v[130:131], v49, off offset:20
	global_atomic_add_f32 v[130:131], v54, off offset:8
	global_atomic_add_f32 v[130:131], v50, off offset:24
	global_atomic_add_f32 v[130:131], v55, off offset:12
	global_atomic_add_f32 v[130:131], v51, off offset:28
	global_atomic_add_f32 v[130:131], v20, off offset:512
	global_atomic_add_f32 v[130:131], v16, off offset:528
	global_atomic_add_f32 v[130:131], v21, off offset:516
	global_atomic_add_f32 v[130:131], v17, off offset:532
	global_atomic_add_f32 v[130:131], v22, off offset:520
	global_atomic_add_f32 v[130:131], v18, off offset:536
	global_atomic_add_f32 v[130:131], v23, off offset:524
	global_atomic_add_f32 v[130:131], v19, off offset:540
	v_add_u32_e32 v130, 0xa0, v128
	v_ashrrev_i32_e32 v131, 31, v130
	v_add_u32_e32 v128, 0xb0, v128
	v_lshl_add_u64 v[130:131], v[130:131], 0, s[78:79]
	v_ashrrev_i32_e32 v129, 31, v128
	v_lshlrev_b64 v[130:131], 12, v[130:131]
	v_lshl_add_u64 v[128:129], v[128:129], 0, s[78:79]
	v_lshl_add_u64 v[130:131], s[82:83], 0, v[130:131]
	v_lshlrev_b64 v[128:129], 12, v[128:129]
	v_lshl_add_u64 v[130:131], v[130:131], 0, s[10:11]
	v_lshl_add_u64 v[128:129], s[82:83], 0, v[128:129]
	v_lshl_add_u64 v[130:131], v[130:131], 0, v[132:133]
	v_lshl_add_u64 v[128:129], v[128:129], 0, s[10:11]
	global_atomic_add_f32 v[130:131], v44, off
	global_atomic_add_f32 v[130:131], v40, off offset:16
	global_atomic_add_f32 v[130:131], v45, off offset:4
	global_atomic_add_f32 v[130:131], v41, off offset:20
	global_atomic_add_f32 v[130:131], v46, off offset:8
	global_atomic_add_f32 v[130:131], v42, off offset:24
	global_atomic_add_f32 v[130:131], v47, off offset:12
	global_atomic_add_f32 v[130:131], v43, off offset:28
	global_atomic_add_f32 v[130:131], v12, off offset:512
	global_atomic_add_f32 v[130:131], v8, off offset:528
	global_atomic_add_f32 v[130:131], v13, off offset:516
	global_atomic_add_f32 v[130:131], v9, off offset:532
	global_atomic_add_f32 v[130:131], v14, off offset:520
	global_atomic_add_f32 v[130:131], v10, off offset:536
	global_atomic_add_f32 v[130:131], v15, off offset:524
	global_atomic_add_f32 v[130:131], v11, off offset:540
	v_lshl_add_u64 v[128:129], v[128:129], 0, v[132:133]
	global_atomic_add_f32 v[128:129], v36, off
	global_atomic_add_f32 v[128:129], v32, off offset:16
	global_atomic_add_f32 v[128:129], v37, off offset:4
	global_atomic_add_f32 v[128:129], v33, off offset:20
	global_atomic_add_f32 v[128:129], v38, off offset:8
	global_atomic_add_f32 v[128:129], v34, off offset:24
	global_atomic_add_f32 v[128:129], v39, off offset:12
	global_atomic_add_f32 v[128:129], v35, off offset:28
	global_atomic_add_f32 v[128:129], v4, off offset:512
	global_atomic_add_f32 v[128:129], v0, off offset:528
	global_atomic_add_f32 v[128:129], v5, off offset:516
	global_atomic_add_f32 v[128:129], v1, off offset:532
	global_atomic_add_f32 v[128:129], v6, off offset:520
	global_atomic_add_f32 v[128:129], v2, off offset:536
	global_atomic_add_f32 v[128:129], v7, off offset:524
	global_atomic_add_f32 v[128:129], v3, off offset:540
